# code placement: the six GEMM K-loop heads at a 64-byte boundary plus 4 bytes
# speedup vs baseline: 1.0011x; 1.0011x over previous
; template <class Epi, class Sched, bool ALIGN_EPI = false, bool SP2 = false>
; __device__ __forceinline__ void gemm_phase(PG8_LAS unsigned char* lds, const Gemm g, const Sched& S, const Epi& E) {
;     ...
;         for (int t = 0; t < nt; t += 2) {
;             const bool last = (t == nt - 2);
.Lprio_done_86:
	.p2align	6
	s_nop 0
